# gla prep work queue: next ticket fetched one item ahead (atomic round trip overlapped with the item)
# baseline (speedup 1.0000x reference)
; #define LAS __attribute__((address_space(3)))
; __device__ __forceinline__ void ph_prep(int l, LAS unsigned char* lds) {
;     LAS int* s_item = (LAS int*)(lds + 150 * 1024);
;     for (;;) { PH_PRE
;         if (tid == 0) *s_item = (int)atomicAdd((unsigned*)(ws + WS_CTL) + CW_Q + 64 * (16 + l), 1u);
;         __syncthreads(); const int it = __builtin_amdgcn_readfirstlane(*s_item); __syncthreads();
.LBB0_1240:
	s_lshl_b32 s10, s77, 6
	s_lshl_b32 s2, s77, 14
	s_mov_b32 s3, s11
	s_lshl_b32 s22, s77, 10
	s_lshl_b64 s[6:7], s[10:11], 2
	s_lshl_b64 s[12:13], s[2:3], 2
	s_movk_i32 s23, 0x100
	s_movk_i32 s30, 0x700
	s_movk_i32 s35, 0x740
	s_movk_i32 s36, 0x6c0
	s_movk_i32 s40, 0x640
	s_movk_i32 s42, 0x1c0
	s_movk_i32 s43, 0x5c0
	s_movk_i32 s48, 0x240
	s_movk_i32 s51, 0x280
	s_movk_i32 s52, 0x2c0
	s_waitcnt lgkmcnt(0)
	s_movk_i32 s54, 0x4c0
	v_cmp_eq_u32_e32 vcc, 0, v206
	s_and_saveexec_b64 s[14:15], vcc
	s_cbranch_execz .Lmy_prep_pf
	s_load_dwordx2 s[16:17], s[0:1], 0xd0
	v_mov_b32_e32 v2, 0x1000
	v_mov_b32_e32 v1, 1
	s_waitcnt lgkmcnt(0)
	s_add_u32 s16, s16, s6
	s_addc_u32 s17, s17, s7
	global_atomic_add v250, v2, v1, s[16:17] offset:256 sc0
	s_waitcnt vmcnt(0)
.Lmy_prep_pf:
	s_or_b64 exec, exec, s[14:15]
	s_branch .LBB0_1243

; #define LAS __attribute__((address_space(3)))
; __device__ __forceinline__ void gla_prep_item(ArgsP a, int l, int item, LAS unsigned char* lds) {
;     ...
;     if (tid < 256) { const int row = tid >> 2, part = tid & 3; *(LAS f32x4*)(gfs + row * 16 + part * 4) = *(const f32x4*)(MISC + (size_t)(base + row) * MISC_LD + dir * 16 + part * 4); }
; __device__ __forceinline__ void ph_prep(int l, LAS unsigned char* lds) {
;     ...
;     for (;;) { PH_PRE
;         if (tid == 0) *s_item = (int)atomicAdd((unsigned*)(ws + WS_CTL) + CW_Q + 64 * (16 + l), 1u);
;         __syncthreads(); const int it = __builtin_amdgcn_readfirstlane(*s_item); __syncthreads();
;         if (it >= NITEM_PREP) break;
;         gla_prep_item(a, l, it, lds); }
.LBB0_1243:
	s_mov_b64 s[18:19], s[0:1]
	v_mov_b32_e32 v0, v206
	s_mov_b32 s2, s8
	v_cmp_eq_u32_e32 vcc, 0, v0
	s_and_saveexec_b64 s[2:3], vcc
	s_cbranch_execz .LBB0_1247
	s_mov_b64 s[14:15], exec
	v_mbcnt_lo_u32_b32 v0, s14, 0
	v_mbcnt_hi_u32_b32 v0, s15, v0
	v_cmp_eq_u32_e32 vcc, 0, v0
	s_and_saveexec_b64 s[4:5], vcc
	s_cbranch_execz .LBB0_1246
	s_load_dwordx2 s[16:17], s[18:19], 0xd0
	v_mov_b32_e32 v2, 0x1000
	s_waitcnt lgkmcnt(0)
	s_add_u32 s16, s16, s6
	s_addc_u32 s17, s17, s7
	s_bcnt1_i32_b64 s10, s[14:15]
	v_mov_b32_e32 v1, s10
	s_waitcnt vmcnt(0)
	v_mov_b32_e32 v3, v250
	global_atomic_add v250, v2, v1, s[16:17] offset:256 sc0
	v_mov_b32_e32 v1, v3
.LBB0_1246:
	s_or_b64 exec, exec, s[4:5]
	v_readfirstlane_b32 s4, v1
	v_mov_b32_e32 v1, s49
	s_nop 0
	v_add_u32_e32 v0, s4, v0
	ds_write_b32 v1, v0
.LBB0_1247:
	s_or_b64 exec, exec, s[2:3]
	v_mov_b32_e32 v0, s49
	s_waitcnt lgkmcnt(0)
	s_barrier
	ds_read_b32 v0, v0
	s_mov_b64 s[2:3], -1
	s_waitcnt lgkmcnt(0)
	s_barrier
	v_readfirstlane_b32 s14, v0
	s_cmpk_gt_i32 s14, 0x47f
	s_cbranch_scc1 .LBB0_1242
	s_mul_hi_i32 s4, s14, 0x38e38e39
	v_mov_b32_e32 v17, v206
	s_ashr_i32 s2, s4, 3
	s_lshr_b32 s5, s4, 31
	s_add_i32 s2, s2, s5
	s_load_dwordx2 s[16:17], s[18:19], 0xd0
	s_mul_i32 s3, s2, 36
	s_and_b32 s15, s2, 1
	s_lshr_b32 s2, s4, 6
	s_sub_i32 s3, s14, s3
	s_add_i32 s2, s2, s5
	s_mul_i32 s20, s2, 0x900
	s_lshl_b32 s2, s3, 6
	s_add_i32 s20, s20, s2
	v_cmp_gt_i32_e32 vcc, s23, v17
	s_and_saveexec_b64 s[2:3], vcc
	s_cbranch_execz .LBB0_1250
	v_ashrrev_i32_e32 v4, 2, v17
	v_add_u32_e32 v2, s20, v4
	s_waitcnt lgkmcnt(0)
	v_mov_b64_e32 v[0:1], s[16:17]
	v_mad_i64_i32 v[0:1], s[24:25], v2, s86, v[0:1]
	s_lshl_b32 s10, s15, 6
	v_lshlrev_b32_e32 v2, 4, v17
	v_lshl_add_u64 v[0:1], v[0:1], 0, s[10:11]
	v_and_b32_e32 v160, 48, v2
	v_lshl_add_u64 v[0:1], v[0:1], 0, v[160:161]
	v_add_co_u32_e32 v0, vcc, 0x300000, v0
	v_lshlrev_b32_e32 v4, 6, v4
	s_nop 0
	v_addc_co_u32_e32 v1, vcc, 0, v1, vcc
	global_load_dwordx4 v[0:3], v[0:1], off
	v_add3_u32 v4, 0, v4, v160
	s_waitcnt vmcnt(0)
	ds_write_b128 v4, v[0:3]
